# barrier census (first barrier only): the 16 per-XCC counter loads issued together instead of one at a time; on top of v136
# baseline (speedup 1.0000x reference)
.LBB0_1484:
	v_readlane_b32 s2, v244, 6
	v_readlane_b32 s3, v244, 7
	global_load_dword v5, v0, s[22:23] sc1
	global_load_dword v1, v0, s[24:25] sc1
	s_waitcnt lgkmcnt(0)
	global_load_dword v2, v0, s[28:29] sc1
	global_load_dword v3, v0, s[34:35] sc1
	global_load_dword v4, v0, s[18:19] sc1
	global_load_dword v6, v0, s[2:3] sc1
	global_load_dword v7, v0, s[22:23] offset:1536 sc1
	global_load_dword v8, v0, s[22:23] offset:1792 sc1
	global_load_dword v9, v0, s[22:23] offset:2048 sc1
	global_load_dword v10, v0, s[22:23] offset:2304 sc1
	global_load_dword v11, v0, s[22:23] offset:2560 sc1
	global_load_dword v12, v0, s[22:23] offset:2816 sc1
	global_load_dword v13, v0, s[22:23] offset:3072 sc1
	global_load_dword v14, v0, s[22:23] offset:3328 sc1
	global_load_dword v15, v0, s[22:23] offset:3584 sc1
	global_load_dword v16, v0, s[22:23] offset:3840 sc1
	s_mov_b64 s[4:5], -1
	s_waitcnt vmcnt(0)
	v_add_u32_e32 v17, v1, v5
	v_add_u32_e32 v17, v17, v2
	v_add_u32_e32 v17, v17, v3
	v_add_u32_e32 v17, v17, v4
	v_add_u32_e32 v17, v17, v6
	v_add_u32_e32 v17, v17, v7
	v_add_u32_e32 v17, v17, v8
	v_add_u32_e32 v17, v17, v9
	v_add_u32_e32 v17, v17, v10
	v_add_u32_e32 v17, v17, v11
	v_add_u32_e32 v17, v17, v12
	v_add_u32_e32 v17, v17, v13
	v_add_u32_e32 v17, v17, v14
	v_add_u32_e32 v17, v17, v15
	v_add_u32_e32 v17, v17, v16
	s_mov_b64 s[2:3], -1
	v_cmp_eq_u32_e32 vcc, s89, v17
	s_cbranch_vccnz .LBB0_1483
	s_and_b32 s2, s8, 0xff
	s_cmp_eq_u32 s2, 0
	s_mov_b64 s[2:3], -1
	s_mov_b64 s[6:7], -1
	s_sleep 1
	s_cbranch_scc0 .LBB0_1488
	global_load_dword v17, v0, s[20:21] sc1
	s_waitcnt vmcnt(0)
	v_cmp_eq_u32_e32 vcc, 0, v17
	s_cbranch_vccnz .LBB0_1490
	s_mov_b64 s[6:7], 0
